# combo29: combo27 + EpiUp: the next unit's row sum-of-squares load (tid < 256) is no longer waited with vmcnt(0) at the start of every epilogue; it lands in free VGPRs and is converted right before its
# baseline (speedup 1.0000x reference)
; __device__ __forceinline__ float rsq_sum(const u64_t* rsq, int row) { return (float)rsq[row] * (1.0f / 16777216.0f); }
; __device__ __forceinline__ float row_rstd(const u64_t* rsq, int row) { return fast_rsq(rsq_sum(rsq, row) * (1.0f / DM) + EPS); }
; #define PG8_EPI_BAR() do { asm volatile("s_waitcnt lgkmcnt(0)" ::: "memory"); __builtin_amdgcn_s_barrier(); asm volatile("" ::: "memory"); } while (0)
;     __device__ __forceinline__ void run(const f32x4 (&acc)[2][2][4][2], const Unit& u, const Unit& nxt, bool has_next, int ui, int wr, int wc, int fr_in, int fq_in) const {
;         int fr = fr_in, fq = fq_in; asm volatile("" : "+v"(fr), "+v"(fq));
;         const int tid = (wr * 4 + wc) * 64 + fq * 16 + fr;
;         const int slot = ui & 1;
;         if (ui == 0) {
;             prm[slot * 1024 + tid] = ldp(tid, u.pn); prm[slot * 1024 + tid + 512] = ldp(tid + 512, u.pn);
;             if (tid < 256) rsd[slot * 256 + tid] = row_rstd(rsq, u.pm * BM + tid);
;             PG8_EPI_BAR();
;         }
;         float nx0 = 0.f, nx1 = 0.f, nrs = 1.f;
;         if (has_next) { nx0 = ldp(tid, nxt.pn); nx1 = ldp(tid + 512, nxt.pn); if (tid < 256) nrs = rsq_sum(rsq, nxt.pm * BM + tid); }
.LBB0_690:
	v_bfe_u32 v73, v226, 7, 2
	v_ashrrev_i32_e32 v72, 9, v226
	v_and_b32_e32 v74, 0x7f, v226
	v_mul_u32_u24_e32 v75, 0x1600, v73
	v_cmp_eq_u32_e32 vcc, 3, v73
	v_add_u32_e32 v102, 0x200, v226
	v_mul_i32_i24_e32 v72, 0xb00, v72
	v_cndmask_b32_e64 v100, v75, 0, vcc
	v_lshl_or_b32 v101, s34, 7, v74
	v_mov_b32_e32 v73, s7
	v_mov_b32_e32 v74, s9
	v_ashrrev_i32_e32 v102, 9, v102
	v_add3_u32 v72, v101, v72, v100
	v_cndmask_b32_e32 v75, v73, v74, vcc
	v_mov_b32_e32 v73, s6
	v_mov_b32_e32 v74, s8
	v_mul_i32_i24_e32 v102, 0xb00, v102
	v_cndmask_b32_e32 v74, v73, v74, vcc
	v_ashrrev_i32_e32 v73, 31, v72
	v_add3_u32 v100, v102, v101, v100
	v_lshl_add_u64 v[72:73], v[72:73], 2, v[74:75]
	v_ashrrev_i32_e32 v101, 31, v100
	v_lshl_add_u64 v[74:75], v[100:101], 2, v[74:75]
	global_load_dword v228, v[72:73], off
	global_load_dword v227, v[74:75], off
	v_cmp_gt_i32_e32 vcc, s65, v226
	v_mov_b32_e32 v229, 0x3a80218e
	s_and_saveexec_b64 s[0:1], vcc
	s_cbranch_execz .LBB0_692
	v_lshl_add_u32 v72, s36, 8, v226
	v_ashrrev_i32_e32 v73, 31, v72
	v_lshl_add_u64 v[72:73], v[72:73], 3, s[22:23]
	global_load_dwordx2 v[198:199], v[72:73], off

; __device__ __forceinline__ unsigned pk2(float lo, float hi) { f32x2_t v = {lo, hi}; bf16x2_t b = __builtin_convertvector(v, bf16x2_t); return __builtin_bit_cast(unsigned, b); }
; #define DPPF(v, ctrl) __builtin_bit_cast(float, __builtin_amdgcn_update_dpp(0, __builtin_bit_cast(int, (v)), (ctrl), 0xf, 0xf, false))
; __device__ __forceinline__ float sigmoidf_(float v) { return fast_rcp(1.0f + fast_exp2(-v * LOG2E)); }
;     __device__ __forceinline__ void run(const f32x4 (&acc)[2][2][4][2], const Unit& u, const Unit& nxt, bool has_next, int ui, int wr, int wc, int fr_in, int fq_in) const {
;     ...
;                 {
;                     const f32x4 g2 = acc[ai][0][2][n] * rs[ai][2], g3 = acc[ai][0][3][n] * rs[ai][3], v2 = acc[ai][1][2][n] * rs[ai][2], v3 = acc[ai][1][3][n] * rs[ai][3];
; #pragma unroll
;                     for (int i = 0; i < 4; ++i) {
;                         float a0 = g2[i], a1 = g3[i], a2 = v2[i], a3 = v3[i];
;                         asm volatile("" : "+v"(a0), "+v"(a1), "+v"(a2), "+v"(a3));
;                         const float t0 = DPPF(a0, 0x111), t1 = DPPF(a1, 0x111), t2 = DPPF(a2, 0x111), t3 = DPPF(a3, 0x111);
;                         pg2[i] = t0 + hg2[i]; pg1[i] = t1 + hg3[i]; pv2[i] = t2 + hv2[i]; pv1[i] = t3 + hv3[i]; }
;                 }
; #pragma unroll
;                 for (int m = 0; m < 4; ++m) {
;                     const f32x4 gc = acc[ai][0][m][n] * rs[ai][m], vc = acc[ai][1][m][n] * rs[ai][m];
;                     const f32x4 cgt = bg + wg0 * pg2 + wg1 * pg1 + wg2 * gc, cvl = bv + wv0 * pv2 + wv1 * pv1 + wv2 * vc;
;                     float a[4];
; #pragma unroll
;                     for (int i = 0; i < 4; ++i) a[i] = cgt[i] * sigmoidf_(cgt[i]) * cvl[i];
;                     u32x2 w; w.x = pk2(a[0], a[1]); w.y = pk2(a[2], a[3]);
;                     *(u32x2*)(A + (size_t)(u.pm * BM + ai * 128 + wr * 64 + 4 * fr + m) * DFF + ch) = w;
;                     pg2 = pg1; pg1 = gc; pv2 = pv1; pv1 = vc;
;                 }
.LBB0_725:
	s_or_b64 exec, exec, s[0:1]
	v_mov_b32_dpp v54, v4 row_shr:1 row_mask:0xf bank_mask:0xf bound_ctrl:1
	v_mov_b32_dpp v58, v8 row_shr:1 row_mask:0xf bank_mask:0xf bound_ctrl:1
	v_mov_b32_dpp v60, v0 row_shr:1 row_mask:0xf bank_mask:0xf bound_ctrl:1
	v_mov_b32_dpp v52, v12 row_shr:1 row_mask:0xf bank_mask:0xf bound_ctrl:1
	v_mov_b32_dpp v53, v13 row_shr:1 row_mask:0xf bank_mask:0xf bound_ctrl:1
	s_waitcnt lgkmcnt(0)
	v_pk_add_f32 v[40:41], v[40:41], v[52:53]
	v_mov_b32_dpp v55, v5 row_shr:1 row_mask:0xf bank_mask:0xf bound_ctrl:1
	v_pk_add_f32 v[36:37], v[36:37], v[54:55]
	v_pk_fma_f32 v[40:41], v[84:85], v[40:41], v[96:97]
	v_pk_fma_f32 v[40:41], v[88:89], v[36:37], v[40:41]
	v_pk_fma_f32 v[40:41], v[28:29], v[92:93], v[40:41]
	v_mov_b32_dpp v59, v9 row_shr:1 row_mask:0xf bank_mask:0xf bound_ctrl:1
	v_exp_f32_e32 v52, v40
	v_exp_f32_e32 v53, v41
	v_mov_b32_dpp v61, v1 row_shr:1 row_mask:0xf bank_mask:0xf bound_ctrl:1
	v_mov_b32_dpp v100, v6 row_shr:1 row_mask:0xf bank_mask:0xf bound_ctrl:1
	v_mov_b32_dpp v102, v10 row_shr:1 row_mask:0xf bank_mask:0xf bound_ctrl:1
	v_mov_b32_dpp v108, v2 row_shr:1 row_mask:0xf bank_mask:0xf bound_ctrl:1
	v_mov_b32_dpp v62, v14 row_shr:1 row_mask:0xf bank_mask:0xf bound_ctrl:1
	v_add_f32_e32 v52, 1.0, v52
	v_add_f32_e32 v53, 1.0, v53
	v_mov_b32_dpp v63, v15 row_shr:1 row_mask:0xf bank_mask:0xf bound_ctrl:1
	v_rcp_f32_e32 v52, v52
	v_rcp_f32_e32 v53, v53
	v_mov_b32_dpp v101, v7 row_shr:1 row_mask:0xf bank_mask:0xf bound_ctrl:1
	v_pk_add_f32 v[42:43], v[42:43], v[62:63]
	v_mov_b32_e32 v111, v72
	v_mov_b32_dpp v103, v11 row_shr:1 row_mask:0xf bank_mask:0xf bound_ctrl:1
	v_pk_add_f32 v[38:39], v[38:39], v[100:101]
	v_pk_fma_f32 v[42:43], v[86:87], v[42:43], v[98:99]
	v_mov_b32_dpp v109, v3 row_shr:1 row_mask:0xf bank_mask:0xf bound_ctrl:1
	v_mov_b32_e32 v110, v72
	v_pk_fma_f32 v[42:43], v[90:91], v[38:39], v[42:43]
	v_pk_mul_f32 v[40:41], v[40:41], v[52:53]
	v_pk_fma_f32 v[42:43], v[30:31], v[94:95], v[42:43]
	v_pk_add_f32 v[32:33], v[32:33], v[58:59]
	v_exp_f32_e32 v52, v42
	v_exp_f32_e32 v53, v43
	v_pk_add_f32 v[48:49], v[104:105], v[60:61]
	v_pk_fma_f32 v[32:33], v[64:65], v[32:33], v[80:81]
	v_add_f32_e32 v52, 1.0, v52
	v_add_f32_e32 v53, 1.0, v53
	v_pk_fma_f32 v[32:33], v[68:69], v[48:49], v[32:33]
	v_rcp_f32_e32 v52, v52
	v_rcp_f32_e32 v53, v53
	v_pk_fma_f32 v[32:33], v[24:25], v[76:77], v[32:33]
	v_pk_add_f32 v[34:35], v[34:35], v[102:103]
	v_pk_mul_f32 v[32:33], v[32:33], v[40:41]
	v_pk_add_f32 v[40:41], v[106:107], v[108:109]
	v_pk_fma_f32 v[34:35], v[66:67], v[34:35], v[82:83]
	v_pk_fma_f32 v[34:35], v[70:71], v[40:41], v[34:35]
	v_pk_mul_f32 v[42:43], v[42:43], v[52:53]
	v_pk_fma_f32 v[34:35], v[26:27], v[78:79], v[34:35]
	v_cvt_pk_bf16_f32 v32, v32, v33
	v_pk_mul_f32 v[34:35], v[34:35], v[42:43]
	v_mov_b32_e32 v50, v73
	v_cvt_pk_bf16_f32 v33, v34, v35
	v_lshl_add_u64 v[34:35], v[122:123], 0, v[56:57]
	v_mov_b32_e32 v51, v73
	global_store_dwordx2 v[34:35], v[32:33], off
	v_pk_fma_f32 v[32:33], v[84:85], v[36:37], v[96:97]
	v_pk_fma_f32 v[32:33], v[28:29], v[88:89], v[32:33]
	v_mov_b32_e32 v72, v73
	v_pk_fma_f32 v[32:33], v[20:21], v[92:93], v[32:33]
	v_exp_f32_e32 v34, v32
	v_exp_f32_e32 v35, v33
	v_mov_b32_e32 v46, v74
	v_mov_b32_e32 v47, v74
	v_add_f32_e32 v34, 1.0, v34
	v_add_f32_e32 v35, 1.0, v35
	v_rcp_f32_e32 v34, v34
	v_rcp_f32_e32 v35, v35
	v_pk_fma_f32 v[28:29], v[28:29], v[84:85], v[96:97]
	v_mov_b32_e32 v44, v75
	v_mov_b32_e32 v45, v75
	v_pk_mul_f32 v[32:33], v[32:33], v[34:35]
	v_pk_fma_f32 v[34:35], v[86:87], v[38:39], v[98:99]
	v_pk_fma_f32 v[34:35], v[30:31], v[90:91], v[34:35]
	v_pk_fma_f32 v[28:29], v[20:21], v[88:89], v[28:29]
	v_pk_fma_f32 v[34:35], v[22:23], v[94:95], v[34:35]
	v_pk_fma_f32 v[20:21], v[20:21], v[84:85], v[96:97]
	v_exp_f32_e32 v38, v34
	v_exp_f32_e32 v39, v35
	v_pk_fma_f32 v[28:29], v[12:13], v[92:93], v[28:29]
	v_pk_fma_f32 v[12:13], v[12:13], v[88:89], v[20:21]
	v_pk_fma_f32 v[36:37], v[64:65], v[48:49], v[80:81]
	v_add_f32_e32 v38, 1.0, v38
	v_add_f32_e32 v39, 1.0, v39
	v_pk_fma_f32 v[4:5], v[4:5], v[92:93], v[12:13]
	v_rcp_f32_e32 v38, v38
	v_rcp_f32_e32 v39, v39
	v_pk_fma_f32 v[36:37], v[24:25], v[68:69], v[36:37]
	v_pk_fma_f32 v[36:37], v[16:17], v[76:77], v[36:37]
	v_exp_f32_e32 v12, v4
	v_exp_f32_e32 v13, v5
	v_pk_mul_f32 v[32:33], v[36:37], v[32:33]
	v_pk_fma_f32 v[36:37], v[66:67], v[40:41], v[82:83]
	v_pk_fma_f32 v[36:37], v[26:27], v[70:71], v[36:37]
	v_pk_mul_f32 v[34:35], v[34:35], v[38:39]
	v_pk_fma_f32 v[36:37], v[18:19], v[78:79], v[36:37]
	v_add_f32_e32 v12, 1.0, v12
	v_pk_mul_f32 v[34:35], v[36:37], v[34:35]
	v_add_f32_e32 v13, 1.0, v13
	v_cvt_pk_bf16_f32 v32, v32, v33
	v_cvt_pk_bf16_f32 v33, v34, v35
	v_lshl_add_u64 v[34:35], v[124:125], 0, v[56:57]
	v_rcp_f32_e32 v12, v12
	v_rcp_f32_e32 v13, v13
	global_store_dwordx2 v[34:35], v[32:33], off
	v_exp_f32_e32 v34, v28
	v_mov_b32_e32 v32, v74
	v_exp_f32_e32 v35, v29
	v_mov_b32_e32 v33, v74
	v_mov_b32_e32 v74, v75
	v_pk_mul_f32 v[4:5], v[4:5], v[12:13]
	v_pk_fma_f32 v[12:13], v[22:23], v[86:87], v[98:99]
	v_pk_fma_f32 v[12:13], v[14:15], v[90:91], v[12:13]
	v_pk_fma_f32 v[30:31], v[30:31], v[86:87], v[98:99]
	v_pk_fma_f32 v[6:7], v[6:7], v[94:95], v[12:13]
	v_pk_fma_f32 v[30:31], v[22:23], v[90:91], v[30:31]
	v_pk_fma_f32 v[30:31], v[14:15], v[94:95], v[30:31]
	v_exp_f32_e32 v14, v6
	v_exp_f32_e32 v15, v7
	v_exp_f32_e32 v32, v30
	v_exp_f32_e32 v33, v31
	v_add_f32_e32 v14, 1.0, v14
	v_add_f32_e32 v15, 1.0, v15
	v_add_f32_e32 v34, 1.0, v34
	v_add_f32_e32 v35, 1.0, v35
	v_pk_fma_f32 v[24:25], v[24:25], v[64:65], v[80:81]
	v_rcp_f32_e32 v14, v14
	v_rcp_f32_e32 v15, v15
	v_rcp_f32_e32 v34, v34
	v_rcp_f32_e32 v35, v35
	v_add_f32_e32 v32, 1.0, v32
	v_add_f32_e32 v33, 1.0, v33
	v_pk_fma_f32 v[24:25], v[16:17], v[68:69], v[24:25]
	v_pk_fma_f32 v[12:13], v[16:17], v[64:65], v[80:81]
	v_rcp_f32_e32 v32, v32
	v_rcp_f32_e32 v33, v33
	v_pk_fma_f32 v[24:25], v[8:9], v[76:77], v[24:25]
	v_pk_fma_f32 v[8:9], v[8:9], v[68:69], v[12:13]
	v_pk_fma_f32 v[26:27], v[26:27], v[66:67], v[82:83]
	v_pk_fma_f32 v[0:1], v[0:1], v[76:77], v[8:9]
	v_pk_mul_f32 v[28:29], v[28:29], v[34:35]
	v_pk_mul_f32 v[0:1], v[0:1], v[4:5]
	v_pk_mul_f32 v[4:5], v[6:7], v[14:15]
	v_pk_fma_f32 v[6:7], v[18:19], v[66:67], v[82:83]
	v_pk_fma_f32 v[26:27], v[18:19], v[70:71], v[26:27]
	v_pk_fma_f32 v[6:7], v[10:11], v[70:71], v[6:7]
	v_pk_mul_f32 v[24:25], v[24:25], v[28:29]
	v_pk_mul_f32 v[28:29], v[30:31], v[32:33]
	v_pk_fma_f32 v[26:27], v[10:11], v[78:79], v[26:27]
	v_pk_fma_f32 v[2:3], v[2:3], v[78:79], v[6:7]
	v_pk_mul_f32 v[26:27], v[26:27], v[28:29]
	v_pk_mul_f32 v[2:3], v[2:3], v[4:5]
	v_cvt_pk_bf16_f32 v24, v24, v25
	v_cvt_pk_bf16_f32 v25, v26, v27
	v_lshl_add_u64 v[26:27], v[130:131], 0, v[56:57]
	v_cvt_pk_bf16_f32 v0, v0, v1
	v_cvt_pk_bf16_f32 v1, v2, v3
	v_lshl_add_u64 v[2:3], v[134:135], 0, v[56:57]
	global_store_dwordx2 v[26:27], v[24:25], off
	global_store_dwordx2 v[2:3], v[0:1], off
	s_and_b64 vcc, exec, s[10:11]
	s_mov_b64 s[0:1], -1
	s_cbranch_vccnz .LBB0_681
; __device__ __forceinline__ float fast_rsq(float x) { return __builtin_amdgcn_rsqf(x); }
; __device__ __forceinline__ float rsq_sum(const u64_t* rsq, int row) { return (float)rsq[row] * (1.0f / 16777216.0f); }
; __device__ __forceinline__ float row_rstd(const u64_t* rsq, int row) { return fast_rsq(rsq_sum(rsq, row) * (1.0f / DM) + EPS); }
;     __device__ __forceinline__ void run(const f32x4 (&acc)[2][2][4][2], const Unit& u, const Unit& nxt, bool has_next, int ui, int wr, int wc, int fr_in, int fq_in) const {
;     ...
;         if (has_next) {
;             prm[(slot ^ 1) * 1024 + tid] = nx0; prm[(slot ^ 1) * 1024 + tid + 512] = nx1;
;             if (tid < 256) rsd[(slot ^ 1) * 256 + tid] = fast_rsq(nrs * (1.0f / DM) + EPS);
;         }
	s_xor_b32 s4, s35, 0x400
	v_lshlrev_b32_e32 v0, 2, v226
	v_lshl_add_u32 v0, s4, 2, v0
	v_add_u32_e32 v0, 0x22040, v0
	v_cmp_gt_i32_e32 vcc, s65, v226
	s_waitcnt vmcnt(0)
	v_mul_f32_e32 v228, 0xbfb8aa3b, v228
	v_mul_f32_e32 v227, 0xbf317218, v227
	ds_write2st64_b32 v0, v228, v227 offset1:8
	s_and_saveexec_b64 s[0:1], vcc
	s_cbranch_execz .LBB0_728
	v_ffbh_u32_e32 v200, v199
	v_min_u32_e32 v200, 32, v200
	v_lshlrev_b64 v[198:199], v200, v[198:199]
	v_min_u32_e32 v198, 1, v198
	v_or_b32_e32 v198, v199, v198
	v_cvt_f32_u32_e32 v198, v198
	v_sub_u32_e32 v199, 32, v200
	v_ldexp_f32 v198, v198, v199
	v_mul_f32_e32 v198, 0x33800000, v198
	v_fmamk_f32 v229, v198, 0x3a800000, v223
	v_rsq_f32_e32 v0, v229
	v_lshl_add_u32 v1, v226, 2, s4
	v_add_u32_e32 v1, 0x24040, v1
	ds_write_b32 v1, v0

; __device__ __forceinline__ float rsq_sum(const u64_t* rsq, int row) { return (float)rsq[row] * (1.0f / 16777216.0f); }
; __device__ __forceinline__ float row_rstd(const u64_t* rsq, int row) { return fast_rsq(rsq_sum(rsq, row) * (1.0f / DM) + EPS); }
; #define PG8_EPI_BAR() do { asm volatile("s_waitcnt lgkmcnt(0)" ::: "memory"); __builtin_amdgcn_s_barrier(); asm volatile("" ::: "memory"); } while (0)
;     __device__ __forceinline__ void run(const f32x4 (&acc)[2][2][4][2], const Unit& u, const Unit& nxt, bool has_next, int ui, int wr, int wc, int fr_in, int fq_in) const {
;         int fr = fr_in, fq = fq_in; asm volatile("" : "+v"(fr), "+v"(fq));
;         const int tid = (wr * 4 + wc) * 64 + fq * 16 + fr;
;         const int slot = ui & 1;
;         if (ui == 0) {
;             prm[slot * 1024 + tid] = ldp(tid, u.pn); prm[slot * 1024 + tid + 512] = ldp(tid + 512, u.pn);
;             if (tid < 256) rsd[slot * 256 + tid] = row_rstd(rsq, u.pm * BM + tid);
;             PG8_EPI_BAR();
;         }
;         float nx0 = 0.f, nx1 = 0.f, nrs = 1.f;
;         if (has_next) { nx0 = ldp(tid, nxt.pn); nx1 = ldp(tid + 512, nxt.pn); if (tid < 256) nrs = rsq_sum(rsq, nxt.pm * BM + tid); }
.LBB0_1552:
	v_bfe_u32 v73, v226, 7, 2
	v_ashrrev_i32_e32 v72, 9, v226
	v_and_b32_e32 v74, 0x7f, v226
	v_mul_u32_u24_e32 v75, 0x1600, v73
	v_cmp_eq_u32_e32 vcc, 3, v73
	v_add_u32_e32 v102, 0x200, v226
	v_mul_i32_i24_e32 v72, 0xb00, v72
	v_cndmask_b32_e64 v100, v75, 0, vcc
	v_lshl_or_b32 v101, s28, 7, v74
	v_mov_b32_e32 v73, s53
	v_mov_b32_e32 v74, s55
	v_ashrrev_i32_e32 v102, 9, v102
	v_add3_u32 v72, v101, v72, v100
	v_cndmask_b32_e32 v75, v73, v74, vcc
	v_mov_b32_e32 v73, s52
	v_mov_b32_e32 v74, s54
	v_mul_i32_i24_e32 v102, 0xb00, v102
	v_cndmask_b32_e32 v74, v73, v74, vcc
	v_ashrrev_i32_e32 v73, 31, v72
	v_add3_u32 v100, v102, v101, v100
	v_lshl_add_u64 v[72:73], v[72:73], 2, v[74:75]
	v_ashrrev_i32_e32 v101, 31, v100
	v_lshl_add_u64 v[74:75], v[100:101], 2, v[74:75]
	global_load_dword v228, v[72:73], off
	global_load_dword v227, v[74:75], off
	v_cmp_gt_i32_e32 vcc, s33, v226
	v_mov_b32_e32 v229, 0x3a80218e
	s_and_saveexec_b64 s[0:1], vcc
	s_cbranch_execz .LBB0_1554
	v_lshl_add_u32 v72, s30, 8, v226
	v_ashrrev_i32_e32 v73, 31, v72
	v_lshl_add_u64 v[72:73], v[72:73], 3, s[18:19]
	global_load_dwordx2 v[198:199], v[72:73], off

; __device__ __forceinline__ unsigned pk2(float lo, float hi) { f32x2_t v = {lo, hi}; bf16x2_t b = __builtin_convertvector(v, bf16x2_t); return __builtin_bit_cast(unsigned, b); }
; #define DPPF(v, ctrl) __builtin_bit_cast(float, __builtin_amdgcn_update_dpp(0, __builtin_bit_cast(int, (v)), (ctrl), 0xf, 0xf, false))
; __device__ __forceinline__ float sigmoidf_(float v) { return fast_rcp(1.0f + fast_exp2(-v * LOG2E)); }
;     __device__ __forceinline__ void run(const f32x4 (&acc)[2][2][4][2], const Unit& u, const Unit& nxt, bool has_next, int ui, int wr, int wc, int fr_in, int fq_in) const {
;     ...
;                 {
;                     const f32x4 g2 = acc[ai][0][2][n] * rs[ai][2], g3 = acc[ai][0][3][n] * rs[ai][3], v2 = acc[ai][1][2][n] * rs[ai][2], v3 = acc[ai][1][3][n] * rs[ai][3];
; #pragma unroll
;                     for (int i = 0; i < 4; ++i) {
;                         float a0 = g2[i], a1 = g3[i], a2 = v2[i], a3 = v3[i];
;                         asm volatile("" : "+v"(a0), "+v"(a1), "+v"(a2), "+v"(a3));
;                         const float t0 = DPPF(a0, 0x111), t1 = DPPF(a1, 0x111), t2 = DPPF(a2, 0x111), t3 = DPPF(a3, 0x111);
;                         pg2[i] = t0 + hg2[i]; pg1[i] = t1 + hg3[i]; pv2[i] = t2 + hv2[i]; pv1[i] = t3 + hv3[i]; }
;                 }
; #pragma unroll
;                 for (int m = 0; m < 4; ++m) {
;                     const f32x4 gc = acc[ai][0][m][n] * rs[ai][m], vc = acc[ai][1][m][n] * rs[ai][m];
;                     const f32x4 cgt = bg + wg0 * pg2 + wg1 * pg1 + wg2 * gc, cvl = bv + wv0 * pv2 + wv1 * pv1 + wv2 * vc;
;                     float a[4];
; #pragma unroll
;                     for (int i = 0; i < 4; ++i) a[i] = cgt[i] * sigmoidf_(cgt[i]) * cvl[i];
;                     u32x2 w; w.x = pk2(a[0], a[1]); w.y = pk2(a[2], a[3]);
;                     *(u32x2*)(A + (size_t)(u.pm * BM + ai * 128 + wr * 64 + 4 * fr + m) * DFF + ch) = w;
;                     pg2 = pg1; pg1 = gc; pv2 = pv1; pv1 = vc;
;                 }
.LBB0_1587:
	s_or_b64 exec, exec, s[0:1]
	v_mov_b32_dpp v54, v4 row_shr:1 row_mask:0xf bank_mask:0xf bound_ctrl:1
	v_mov_b32_dpp v58, v8 row_shr:1 row_mask:0xf bank_mask:0xf bound_ctrl:1
	v_mov_b32_dpp v60, v0 row_shr:1 row_mask:0xf bank_mask:0xf bound_ctrl:1
	v_mov_b32_dpp v52, v12 row_shr:1 row_mask:0xf bank_mask:0xf bound_ctrl:1
	v_mov_b32_dpp v53, v13 row_shr:1 row_mask:0xf bank_mask:0xf bound_ctrl:1
	s_waitcnt lgkmcnt(0)
	v_pk_add_f32 v[40:41], v[40:41], v[52:53]
	v_mov_b32_dpp v55, v5 row_shr:1 row_mask:0xf bank_mask:0xf bound_ctrl:1
	v_pk_add_f32 v[36:37], v[36:37], v[54:55]
	v_pk_fma_f32 v[40:41], v[84:85], v[40:41], v[96:97]
	v_pk_fma_f32 v[40:41], v[88:89], v[36:37], v[40:41]
	v_pk_fma_f32 v[40:41], v[28:29], v[92:93], v[40:41]
	v_mov_b32_dpp v59, v9 row_shr:1 row_mask:0xf bank_mask:0xf bound_ctrl:1
	v_exp_f32_e32 v52, v40
	v_exp_f32_e32 v53, v41
	v_mov_b32_dpp v61, v1 row_shr:1 row_mask:0xf bank_mask:0xf bound_ctrl:1
	v_mov_b32_dpp v100, v6 row_shr:1 row_mask:0xf bank_mask:0xf bound_ctrl:1
	v_mov_b32_dpp v102, v10 row_shr:1 row_mask:0xf bank_mask:0xf bound_ctrl:1
	v_mov_b32_dpp v108, v2 row_shr:1 row_mask:0xf bank_mask:0xf bound_ctrl:1
	v_mov_b32_dpp v62, v14 row_shr:1 row_mask:0xf bank_mask:0xf bound_ctrl:1
	v_add_f32_e32 v52, 1.0, v52
	v_add_f32_e32 v53, 1.0, v53
	v_mov_b32_dpp v63, v15 row_shr:1 row_mask:0xf bank_mask:0xf bound_ctrl:1
	v_rcp_f32_e32 v52, v52
	v_rcp_f32_e32 v53, v53
	v_mov_b32_dpp v101, v7 row_shr:1 row_mask:0xf bank_mask:0xf bound_ctrl:1
	v_pk_add_f32 v[42:43], v[42:43], v[62:63]
	v_mov_b32_e32 v111, v72
	v_mov_b32_dpp v103, v11 row_shr:1 row_mask:0xf bank_mask:0xf bound_ctrl:1
	v_pk_add_f32 v[38:39], v[38:39], v[100:101]
	v_pk_fma_f32 v[42:43], v[86:87], v[42:43], v[98:99]
	v_mov_b32_dpp v109, v3 row_shr:1 row_mask:0xf bank_mask:0xf bound_ctrl:1
	v_mov_b32_e32 v110, v72
	v_pk_fma_f32 v[42:43], v[90:91], v[38:39], v[42:43]
	v_pk_mul_f32 v[40:41], v[40:41], v[52:53]
	v_pk_fma_f32 v[42:43], v[30:31], v[94:95], v[42:43]
	v_pk_add_f32 v[32:33], v[32:33], v[58:59]
	v_exp_f32_e32 v52, v42
	v_exp_f32_e32 v53, v43
	v_pk_add_f32 v[48:49], v[104:105], v[60:61]
	v_pk_fma_f32 v[32:33], v[64:65], v[32:33], v[80:81]
	v_add_f32_e32 v52, 1.0, v52
	v_add_f32_e32 v53, 1.0, v53
	v_pk_fma_f32 v[32:33], v[68:69], v[48:49], v[32:33]
	v_rcp_f32_e32 v52, v52
	v_rcp_f32_e32 v53, v53
	v_pk_fma_f32 v[32:33], v[24:25], v[76:77], v[32:33]
	v_pk_add_f32 v[34:35], v[34:35], v[102:103]
	v_pk_mul_f32 v[32:33], v[32:33], v[40:41]
	v_pk_add_f32 v[40:41], v[106:107], v[108:109]
	v_pk_fma_f32 v[34:35], v[66:67], v[34:35], v[82:83]
	v_pk_fma_f32 v[34:35], v[70:71], v[40:41], v[34:35]
	v_pk_mul_f32 v[42:43], v[42:43], v[52:53]
	v_pk_fma_f32 v[34:35], v[26:27], v[78:79], v[34:35]
	v_cvt_pk_bf16_f32 v32, v32, v33
	v_pk_mul_f32 v[34:35], v[34:35], v[42:43]
	v_mov_b32_e32 v50, v73
	v_cvt_pk_bf16_f32 v33, v34, v35
	v_lshl_add_u64 v[34:35], v[122:123], 0, v[56:57]
	v_mov_b32_e32 v51, v73
	global_store_dwordx2 v[34:35], v[32:33], off
	v_pk_fma_f32 v[32:33], v[84:85], v[36:37], v[96:97]
	v_pk_fma_f32 v[32:33], v[28:29], v[88:89], v[32:33]
	v_mov_b32_e32 v72, v73
	v_pk_fma_f32 v[32:33], v[20:21], v[92:93], v[32:33]
	v_exp_f32_e32 v34, v32
	v_exp_f32_e32 v35, v33
	v_mov_b32_e32 v46, v74
	v_mov_b32_e32 v47, v74
	v_add_f32_e32 v34, 1.0, v34
	v_add_f32_e32 v35, 1.0, v35
	v_rcp_f32_e32 v34, v34
	v_rcp_f32_e32 v35, v35
	v_pk_fma_f32 v[28:29], v[28:29], v[84:85], v[96:97]
	v_mov_b32_e32 v44, v75
	v_mov_b32_e32 v45, v75
	v_pk_mul_f32 v[32:33], v[32:33], v[34:35]
	v_pk_fma_f32 v[34:35], v[86:87], v[38:39], v[98:99]
	v_pk_fma_f32 v[34:35], v[30:31], v[90:91], v[34:35]
	v_pk_fma_f32 v[28:29], v[20:21], v[88:89], v[28:29]
	v_pk_fma_f32 v[34:35], v[22:23], v[94:95], v[34:35]
	v_pk_fma_f32 v[20:21], v[20:21], v[84:85], v[96:97]
	v_exp_f32_e32 v38, v34
	v_exp_f32_e32 v39, v35
	v_pk_fma_f32 v[28:29], v[12:13], v[92:93], v[28:29]
	v_pk_fma_f32 v[12:13], v[12:13], v[88:89], v[20:21]
	v_pk_fma_f32 v[36:37], v[64:65], v[48:49], v[80:81]
	v_add_f32_e32 v38, 1.0, v38
	v_add_f32_e32 v39, 1.0, v39
	v_pk_fma_f32 v[4:5], v[4:5], v[92:93], v[12:13]
	v_rcp_f32_e32 v38, v38
	v_rcp_f32_e32 v39, v39
	v_pk_fma_f32 v[36:37], v[24:25], v[68:69], v[36:37]
	v_pk_fma_f32 v[36:37], v[16:17], v[76:77], v[36:37]
	v_exp_f32_e32 v12, v4
	v_exp_f32_e32 v13, v5
	v_pk_mul_f32 v[32:33], v[36:37], v[32:33]
	v_pk_fma_f32 v[36:37], v[66:67], v[40:41], v[82:83]
	v_pk_fma_f32 v[36:37], v[26:27], v[70:71], v[36:37]
	v_pk_mul_f32 v[34:35], v[34:35], v[38:39]
	v_pk_fma_f32 v[36:37], v[18:19], v[78:79], v[36:37]
	v_add_f32_e32 v12, 1.0, v12
	v_pk_mul_f32 v[34:35], v[36:37], v[34:35]
	v_add_f32_e32 v13, 1.0, v13
	v_cvt_pk_bf16_f32 v32, v32, v33
	v_cvt_pk_bf16_f32 v33, v34, v35
	v_lshl_add_u64 v[34:35], v[124:125], 0, v[56:57]
	v_rcp_f32_e32 v12, v12
	v_rcp_f32_e32 v13, v13
	global_store_dwordx2 v[34:35], v[32:33], off
	v_exp_f32_e32 v34, v28
	v_mov_b32_e32 v32, v74
	v_exp_f32_e32 v35, v29
	v_mov_b32_e32 v33, v74
	v_mov_b32_e32 v74, v75
	v_pk_mul_f32 v[4:5], v[4:5], v[12:13]
	v_pk_fma_f32 v[12:13], v[22:23], v[86:87], v[98:99]
	v_pk_fma_f32 v[12:13], v[14:15], v[90:91], v[12:13]
	v_pk_fma_f32 v[30:31], v[30:31], v[86:87], v[98:99]
	v_pk_fma_f32 v[6:7], v[6:7], v[94:95], v[12:13]
	v_pk_fma_f32 v[30:31], v[22:23], v[90:91], v[30:31]
	v_pk_fma_f32 v[30:31], v[14:15], v[94:95], v[30:31]
	v_exp_f32_e32 v14, v6
	v_exp_f32_e32 v15, v7
	v_exp_f32_e32 v32, v30
	v_exp_f32_e32 v33, v31
	v_add_f32_e32 v14, 1.0, v14
	v_add_f32_e32 v15, 1.0, v15
	v_add_f32_e32 v34, 1.0, v34
	v_add_f32_e32 v35, 1.0, v35
	v_pk_fma_f32 v[24:25], v[24:25], v[64:65], v[80:81]
	v_rcp_f32_e32 v14, v14
	v_rcp_f32_e32 v15, v15
	v_rcp_f32_e32 v34, v34
	v_rcp_f32_e32 v35, v35
	v_add_f32_e32 v32, 1.0, v32
	v_add_f32_e32 v33, 1.0, v33
	v_pk_fma_f32 v[24:25], v[16:17], v[68:69], v[24:25]
	v_pk_fma_f32 v[12:13], v[16:17], v[64:65], v[80:81]
	v_rcp_f32_e32 v32, v32
	v_rcp_f32_e32 v33, v33
	v_pk_fma_f32 v[24:25], v[8:9], v[76:77], v[24:25]
	v_pk_fma_f32 v[8:9], v[8:9], v[68:69], v[12:13]
	v_pk_fma_f32 v[26:27], v[26:27], v[66:67], v[82:83]
	v_pk_fma_f32 v[0:1], v[0:1], v[76:77], v[8:9]
	v_pk_mul_f32 v[28:29], v[28:29], v[34:35]
	v_pk_mul_f32 v[0:1], v[0:1], v[4:5]
	v_pk_mul_f32 v[4:5], v[6:7], v[14:15]
	v_pk_fma_f32 v[6:7], v[18:19], v[66:67], v[82:83]
	v_pk_fma_f32 v[26:27], v[18:19], v[70:71], v[26:27]
	v_pk_fma_f32 v[6:7], v[10:11], v[70:71], v[6:7]
	v_pk_mul_f32 v[24:25], v[24:25], v[28:29]
	v_pk_mul_f32 v[28:29], v[30:31], v[32:33]
	v_pk_fma_f32 v[26:27], v[10:11], v[78:79], v[26:27]
	v_pk_fma_f32 v[2:3], v[2:3], v[78:79], v[6:7]
	v_pk_mul_f32 v[26:27], v[26:27], v[28:29]
	v_pk_mul_f32 v[2:3], v[2:3], v[4:5]
	v_cvt_pk_bf16_f32 v24, v24, v25
	v_cvt_pk_bf16_f32 v25, v26, v27
	v_lshl_add_u64 v[26:27], v[130:131], 0, v[56:57]
	v_cvt_pk_bf16_f32 v0, v0, v1
	v_cvt_pk_bf16_f32 v1, v2, v3
	v_lshl_add_u64 v[2:3], v[134:135], 0, v[56:57]
	global_store_dwordx2 v[26:27], v[24:25], off
	global_store_dwordx2 v[2:3], v[0:1], off
	s_and_b64 vcc, exec, s[6:7]
	s_mov_b64 s[0:1], -1
	s_cbranch_vccnz .LBB0_1543
; __device__ __forceinline__ float fast_rsq(float x) { return __builtin_amdgcn_rsqf(x); }
; __device__ __forceinline__ float rsq_sum(const u64_t* rsq, int row) { return (float)rsq[row] * (1.0f / 16777216.0f); }
; __device__ __forceinline__ float row_rstd(const u64_t* rsq, int row) { return fast_rsq(rsq_sum(rsq, row) * (1.0f / DM) + EPS); }
;     __device__ __forceinline__ void run(const f32x4 (&acc)[2][2][4][2], const Unit& u, const Unit& nxt, bool has_next, int ui, int wr, int wc, int fr_in, int fq_in) const {
;     ...
;         if (has_next) {
;             prm[(slot ^ 1) * 1024 + tid] = nx0; prm[(slot ^ 1) * 1024 + tid + 512] = nx1;
;             if (tid < 256) rsd[(slot ^ 1) * 256 + tid] = fast_rsq(nrs * (1.0f / DM) + EPS);
;         }
	s_xor_b32 s4, s29, 0x400
	v_lshlrev_b32_e32 v0, 2, v226
	v_lshl_add_u32 v0, s4, 2, v0
	v_add_u32_e32 v0, 0x22040, v0
	v_cmp_gt_i32_e32 vcc, s33, v226
	s_waitcnt vmcnt(0)
	v_mul_f32_e32 v228, 0xbfb8aa3b, v228
	v_mul_f32_e32 v227, 0xbf317218, v227
	ds_write2st64_b32 v0, v228, v227 offset1:8
	s_and_saveexec_b64 s[0:1], vcc
	s_cbranch_execz .LBB0_1590
	v_ffbh_u32_e32 v200, v199
	v_min_u32_e32 v200, 32, v200
	v_lshlrev_b64 v[198:199], v200, v[198:199]
	v_min_u32_e32 v198, 1, v198
	v_or_b32_e32 v198, v199, v198
	v_cvt_f32_u32_e32 v198, v198
	v_sub_u32_e32 v199, 32, v200
	v_ldexp_f32 v198, v198, v199
	v_mul_f32_e32 v198, 0x33800000, v198
	v_fmamk_f32 v229, v198, 0x3a800000, v223
	v_rsq_f32_e32 v0, v229
	v_lshl_add_u32 v1, v226, 2, s4
	v_add_u32_e32 v1, 0x24040, v1
	ds_write_b32 v1, v0
